# MLA attention inner loop hand-rescheduled: pipelined LDS fragment reads, softmax VALU interleaved with MFMA, q_rope kept in registers
# speedup vs baseline: 1.0448x; 1.0448x over previous
.LBB0_42:
	v_add_u32_e32 v166, 0x8000, v166
	v_add_u32_e32 v167, 0x8000, v168
	v_add_u32_e32 v168, 0x8000, v170
	v_add_u32_e32 v169, 0x8000, v172
	v_add_u32_e32 v170, 0x8000, v174
	v_add_u32_e32 v171, 0x8000, v176
	v_add_u32_e32 v172, 0x8000, v178
	v_add_u32_e32 v173, 0x8000, v180
	v_mov_b32_e32 v174, v183
	v_mov_b32_e32 v175, v193
	v_mov_b32_e32 v176, v195
	v_mov_b32_e32 v177, v197
	v_mov_b32_e32 v178, v140
	v_mov_b32_e32 v179, v142
	v_add_u32_e32 v180, 0x100, v138
	v_add_u32_e32 v181, 0x180, v138
	v_mov_b32_e32 v182, v136
	s_add_u32 s98, s74, 0x13480000
	s_addc_u32 s99, s75, 0
	s_add_u32 s100, s74, 0xae04000
	s_addc_u32 s101, s75, 0
	v_mov_b32_e32 v144, v158
	v_mov_b32_e32 v145, v159
	v_mov_b32_e32 v146, v156
	v_mov_b32_e32 v147, v157
	v_mov_b32_e32 v148, v154
	v_mov_b32_e32 v149, v155
	v_mov_b32_e32 v150, v152
	v_mov_b32_e32 v151, v153
	v_mov_b32_e32 v152, v134
	v_mov_b32_e32 v153, v135
	v_mov_b32_e32 v154, v132
	v_mov_b32_e32 v155, v133
	v_mov_b32_e32 v156, v130
	v_mov_b32_e32 v157, v131
	v_mov_b32_e32 v158, v128
	v_mov_b32_e32 v159, v129
	v_mov_b32_e32 v192, v222
	v_mov_b32_e32 v128, v236
	v_mov_b32_e32 v129, v238
	v_mov_b32_e32 v130, v234
	v_mov_b32_e32 v131, v237
	v_mov_b32_e32 v132, v233
	v_mov_b32_e32 v133, v235
	v_mov_b32_e32 v134, v231
	v_mov_b32_e32 v135, v232
	v_mov_b32_e32 v136, v228
	v_mov_b32_e32 v137, v230
	v_mov_b32_e32 v138, v227
	v_mov_b32_e32 v139, v229
	v_mov_b32_e32 v140, v224
	v_mov_b32_e32 v141, v226
	v_mov_b32_e32 v142, v223
	v_mov_b32_e32 v143, v225
	ds_read_b128 v[246:249], v164
	ds_read_b128 v[250:253], v164 offset:1024
	ds_read_b128 v[186:189], v164 offset:2048
	ds_read_b128 v[238:241], v164 offset:3072
	s_waitcnt lgkmcnt(0)
.Lmla_loop:
	ds_read_b128 v[214:217], v166 offset:32768
	ds_read_b128 v[218:221], v166 offset:40960
	ds_read_b128 v[222:225], v167 offset:32768
	ds_read_b128 v[226:229], v167 offset:40960
	ds_read_b128 v[230:233], v168 offset:32768
	ds_read_b128 v[234:237], v168 offset:40960
	v_lshl_add_u32 v183, s52, 14, v161
	s_mov_b32 m0, s45
	s_lshl_b32 s8, s49, 14
	global_load_lds_dwordx4 v178, s[98:99]
	v_exp_f32_e32 v144, v144
	v_add_f32_e32 v199, v128, v129
	v_add_f32_e32 v200, v130, v131
	v_exp_f32_e32 v145, v145
	s_waitcnt lgkmcnt(4)
	v_mfma_f32_32x32x16_bf16 v[64:79], v[214:217], v[124:127], 0
	s_mov_b32 m0, s77
	s_add_i32 s12, s8, s44
	global_load_lds_dwordx4 v179, s[98:99]
	v_cvt_pk_bf16_f32 v128, v128, v129
	v_add_f32_e32 v199, v132, v199
	v_exp_f32_e32 v146, v146
	v_mfma_f32_32x32x16_bf16 v[80:95], v[218:221], v[124:127], 0
	ds_read_b128 v[214:217], v169 offset:32768
	ds_read_b128 v[218:221], v169 offset:40960
	v_cvt_pk_bf16_f32 v129, v130, v131
	v_add_f32_e32 v200, v133, v200
	v_exp_f32_e32 v147, v147
	s_waitcnt lgkmcnt(4)
	v_mfma_f32_32x32x16_bf16 v[64:79], v[222:225], v[120:123], v[64:79]
	s_mov_b32 m0, s12
	s_add_i32 s12, s8, s47
	global_load_lds_dwordx4 v180, s[98:99]
	v_add_f32_e32 v199, v134, v199
	v_cvt_pk_bf16_f32 v130, v132, v133
	v_exp_f32_e32 v148, v148
	v_mfma_f32_32x32x16_bf16 v[80:95], v[226:229], v[120:123], v[80:95]
	ds_read_b128 v[222:225], v170 offset:32768
	ds_read_b128 v[226:229], v170 offset:40960
	v_add_f32_e32 v200, v135, v200
	v_exp_f32_e32 v149, v149
	v_add_f32_e32 v199, v136, v199
	s_waitcnt lgkmcnt(4)
	v_mfma_f32_32x32x16_bf16 v[64:79], v[230:233], v[116:119], v[64:79]
	s_mov_b32 m0, s12
	s_nop 0
	global_load_lds_dwordx4 v181, s[98:99]
	v_cvt_pk_bf16_f32 v131, v134, v135
	v_exp_f32_e32 v150, v150
	v_add_f32_e32 v200, v137, v200
	v_mfma_f32_32x32x16_bf16 v[80:95], v[234:237], v[116:119], v[80:95]
	ds_read_b128 v[230:233], v171 offset:32768
	ds_read_b128 v[234:237], v171 offset:40960
	v_exp_f32_e32 v151, v151
	v_add_f32_e32 v199, v138, v199
	v_permlane32_swap_b32_e32 v128, v130
	s_waitcnt lgkmcnt(4)
	v_mfma_f32_32x32x16_bf16 v[64:79], v[214:217], v[112:115], v[64:79]
	s_mov_b32 m0, s9
	s_nop 0
	global_load_lds_dwordx4 v182, s[100:101]
	s_add_u32 s98, s98, 0x40000
	s_addc_u32 s99, s99, 0
	s_add_u32 s100, s100, 0x2000
	s_addc_u32 s101, s101, 0
	v_cvt_pk_bf16_f32 v132, v136, v137
	v_exp_f32_e32 v152, v152
	v_add_f32_e32 v200, v139, v200
	v_mfma_f32_32x32x16_bf16 v[80:95], v[218:221], v[112:115], v[80:95]
	ds_read_b128 v[214:217], v172 offset:32768
	ds_read_b128 v[218:221], v172 offset:40960
	v_exp_f32_e32 v153, v153
	v_add_f32_e32 v199, v140, v199
	v_permlane32_swap_b32_e32 v129, v131
	s_waitcnt lgkmcnt(4)
	v_mfma_f32_32x32x16_bf16 v[64:79], v[222:225], v[108:111], v[64:79]
	v_cvt_pk_bf16_f32 v133, v138, v139
	v_add_f32_e32 v200, v141, v200
	v_exp_f32_e32 v154, v154
	v_mfma_f32_32x32x16_bf16 v[80:95], v[226:229], v[108:111], v[80:95]
	ds_read_b128 v[222:225], v173 offset:32768
	ds_read_b128 v[226:229], v173 offset:40960
	v_add_f32_e32 v199, v142, v199
	v_exp_f32_e32 v155, v155
	v_cvt_pk_bf16_f32 v134, v140, v141
	s_waitcnt lgkmcnt(4)
	v_mfma_f32_32x32x16_bf16 v[64:79], v[230:233], v[104:107], v[64:79]
	v_add_f32_e32 v200, v143, v200
	v_exp_f32_e32 v156, v156
	v_add_f32_e32 v199, v144, v199
	v_mfma_f32_32x32x16_bf16 v[80:95], v[234:237], v[104:107], v[80:95]
	ds_read_b128 v[230:233], v174 offset:8192
	ds_read_b128 v[234:237], v174 offset:12288
	v_cvt_pk_bf16_f32 v135, v142, v143
	v_exp_f32_e32 v157, v157
	v_add_f32_e32 v200, v145, v200
	s_waitcnt lgkmcnt(4)
	v_mfma_f32_32x32x16_bf16 v[64:79], v[214:217], v[100:103], v[64:79]
	v_exp_f32_e32 v158, v158
	v_add_f32_e32 v199, v146, v199
	v_permlane32_swap_b32_e32 v132, v134
	v_mfma_f32_32x32x16_bf16 v[80:95], v[218:221], v[100:103], v[80:95]
	ds_read_b128 v[214:217], v175 offset:8192
	ds_read_b128 v[218:221], v175 offset:12288
	v_cvt_pk_bf16_f32 v144, v144, v145
	v_exp_f32_e32 v159, v159
	v_add_f32_e32 v200, v147, v200
	s_waitcnt lgkmcnt(4)
	v_mfma_f32_32x32x16_bf16 v[64:79], v[222:225], v[96:99], v[64:79]
	v_add_f32_e32 v199, v148, v199
	v_permlane32_swap_b32_e32 v133, v135
	v_cvt_pk_bf16_f32 v145, v146, v147
	v_add_f32_e32 v200, v149, v200
	v_mfma_f32_32x32x16_bf16 v[80:95], v[226:229], v[96:99], v[80:95]
	ds_read_b128 v[222:225], v176 offset:8192
	ds_read_b128 v[226:229], v176 offset:12288
	v_add_f32_e32 v199, v150, v199
	v_cvt_pk_bf16_f32 v146, v148, v149
	v_add_f32_e32 v200, v151, v200
	v_add_f32_e32 v199, v152, v199
	s_waitcnt lgkmcnt(4)
	v_mfma_f32_32x32x16_bf16 v[64:79], v[230:233], v[246:249], v[64:79]
	v_cvt_pk_bf16_f32 v147, v150, v151
	v_add_f32_e32 v200, v153, v200
	v_add_f32_e32 v199, v154, v199
	v_permlane32_swap_b32_e32 v144, v146
	v_mfma_f32_32x32x16_bf16 v[80:95], v[234:237], v[246:249], v[80:95]
	ds_read_b128 v[230:233], v177 offset:8192
	ds_read_b128 v[234:237], v177 offset:12288
	v_cvt_pk_bf16_f32 v148, v152, v153
	v_add_f32_e32 v200, v155, v200
	v_add_f32_e32 v199, v156, v199
	v_permlane32_swap_b32_e32 v145, v147
	s_waitcnt lgkmcnt(4)
	v_mfma_f32_32x32x16_bf16 v[64:79], v[214:217], v[250:253], v[64:79]
	v_cvt_pk_bf16_f32 v149, v154, v155
	v_add_f32_e32 v200, v157, v200
	v_add_f32_e32 v199, v158, v199
	v_cvt_pk_bf16_f32 v150, v156, v157
	v_mfma_f32_32x32x16_bf16 v[80:95], v[218:221], v[250:253], v[80:95]
	ds_read_b64_tr_b16 v[214:215], v183
	ds_read_b64_tr_b16 v[216:217], v183 offset:2048
	ds_read_b64_tr_b16 v[218:219], v183 offset:4096
	ds_read_b64_tr_b16 v[220:221], v183 offset:6144
	v_add_f32_e32 v200, v159, v200
	v_cvt_pk_bf16_f32 v151, v158, v159
	v_permlane32_swap_b32_e32 v148, v150
	v_add_f32_e32 v199, v199, v200
	s_waitcnt lgkmcnt(6)
	v_mfma_f32_32x32x16_bf16 v[64:79], v[222:225], v[186:189], v[64:79]
	v_permlane32_swap_b32_e32 v149, v151
	v_mov_b32_e32 v200, v199
	v_mfma_f32_32x32x16_bf16 v[80:95], v[226:229], v[186:189], v[80:95]
	ds_read_b64_tr_b16 v[222:223], v183 offset:8192
	ds_read_b64_tr_b16 v[224:225], v183 offset:10240
	ds_read_b64_tr_b16 v[226:227], v183 offset:12288
	ds_read_b64_tr_b16 v[228:229], v183 offset:14336
	v_permlane32_swap_b32_e32 v199, v200
	v_add_f32_e32 v199, v199, v200
	v_fma_f32 v163, v163, v198, v199
	s_waitcnt lgkmcnt(8)
	v_mfma_f32_32x32x16_bf16 v[64:79], v[230:233], v[238:241], v[64:79]
	v_mfma_f32_32x32x16_bf16 v[80:95], v[234:237], v[238:241], v[80:95]
	s_waitcnt lgkmcnt(6)
	v_mfma_f32_32x32x16_bf16 v[0:15], v[128:131], v[214:217], v[0:15]
	ds_read_b64_tr_b16 v[136:137], v183 offset:512
	ds_read_b64_tr_b16 v[138:139], v183 offset:2560
	s_waitcnt lgkmcnt(6)
	v_mfma_f32_32x32x16_bf16 v[0:15], v[132:135], v[218:221], v[0:15]
	ds_read_b64_tr_b16 v[140:141], v183 offset:4608
	ds_read_b64_tr_b16 v[142:143], v183 offset:6656
	s_waitcnt lgkmcnt(6)
	v_mfma_f32_32x32x16_bf16 v[0:15], v[144:147], v[222:225], v[0:15]
	ds_read_b64_tr_b16 v[152:153], v183 offset:8704
	ds_read_b64_tr_b16 v[154:155], v183 offset:10752
	v_max3_f32 v196, v64, v65, v66
	v_max3_f32 v197, v80, v81, v82
	v_max3_f32 v196, v196, v67, v68
	v_max3_f32 v197, v197, v83, v84
	v_max3_f32 v196, v196, v69, v70
	v_max3_f32 v197, v197, v85, v86
	s_waitcnt lgkmcnt(6)
	v_mfma_f32_32x32x16_bf16 v[0:15], v[148:151], v[226:229], v[0:15]
	ds_read_b64_tr_b16 v[156:157], v183 offset:12800
	ds_read_b64_tr_b16 v[158:159], v183 offset:14848
	v_max3_f32 v196, v196, v71, v72
	v_max3_f32 v197, v197, v87, v88
	v_max3_f32 v196, v196, v73, v74
	v_max3_f32 v197, v197, v89, v90
	v_max3_f32 v196, v196, v75, v76
	v_max3_f32 v197, v197, v91, v92
	s_waitcnt lgkmcnt(6)
	v_mfma_f32_32x32x16_bf16 v[48:63], v[128:131], v[136:139], v[48:63]
	ds_read_b64_tr_b16 v[214:215], v183 offset:1024
	ds_read_b64_tr_b16 v[216:217], v183 offset:3072
	v_max3_f32 v196, v196, v77, v78
	v_max3_f32 v197, v197, v93, v94
	v_max_f32_e32 v196, v196, v79
	v_max_f32_e32 v197, v197, v95
	v_max_f32_e32 v196, v196, v197
	v_mov_b32_e32 v197, v196
	s_waitcnt lgkmcnt(6)
	v_mfma_f32_32x32x16_bf16 v[48:63], v[132:135], v[140:143], v[48:63]
	ds_read_b64_tr_b16 v[218:219], v183 offset:5120
	ds_read_b64_tr_b16 v[220:221], v183 offset:7168
	v_permlane32_swap_b32_e32 v196, v197
	v_max_f32_e32 v196, v196, v197
	v_sub_f32_e32 v197, v196, v192
	v_cmp_ge_f32_e32 vcc, s97, v197
	s_cmp_eq_u64 vcc, exec
	s_cselect_b64 s[42:43], -1, 0
	s_waitcnt lgkmcnt(6)
	v_mfma_f32_32x32x16_bf16 v[48:63], v[144:147], v[152:155], v[48:63]
	ds_read_b64_tr_b16 v[222:223], v183 offset:9216
	ds_read_b64_tr_b16 v[224:225], v183 offset:11264
	v_max_f32_e32 v196, v192, v196
	v_sub_f32_e32 v197, v192, v196
	v_mul_f32_e32 v197, 0x3dd53b94, v197
	v_exp_f32_e32 v197, v197
	v_cndmask_b32_e64 v192, v196, v192, s[42:43]
	s_waitcnt lgkmcnt(6)
	v_mfma_f32_32x32x16_bf16 v[48:63], v[148:151], v[156:159], v[48:63]
	ds_read_b64_tr_b16 v[226:227], v183 offset:13312
	ds_read_b64_tr_b16 v[228:229], v183 offset:15360
	v_cndmask_b32_e64 v193, v197, 1.0, s[42:43]
	v_mul_f32_e32 v195, 0xbdd53b94, v192
	v_cmp_gt_f32_e64 s[12:13], 1.0, v193
	v_fmamk_f32 v64, v64, 0x3dd53b94, v195
	v_fmamk_f32 v65, v65, 0x3dd53b94, v195
	v_fmamk_f32 v66, v66, 0x3dd53b94, v195
	s_waitcnt lgkmcnt(6)
	v_mfma_f32_32x32x16_bf16 v[32:47], v[128:131], v[214:217], v[32:47]
	ds_read_b64_tr_b16 v[136:137], v183 offset:1536
	ds_read_b64_tr_b16 v[138:139], v183 offset:3584
	v_fmamk_f32 v67, v67, 0x3dd53b94, v195
	v_fmamk_f32 v68, v68, 0x3dd53b94, v195
	v_fmamk_f32 v69, v69, 0x3dd53b94, v195
	v_fmamk_f32 v70, v70, 0x3dd53b94, v195
	v_fmamk_f32 v71, v71, 0x3dd53b94, v195
	v_fmamk_f32 v72, v72, 0x3dd53b94, v195
	s_waitcnt lgkmcnt(6)
	v_mfma_f32_32x32x16_bf16 v[32:47], v[132:135], v[218:221], v[32:47]
	ds_read_b64_tr_b16 v[140:141], v183 offset:5632
	ds_read_b64_tr_b16 v[142:143], v183 offset:7680
	v_fmamk_f32 v73, v73, 0x3dd53b94, v195
	v_fmamk_f32 v74, v74, 0x3dd53b94, v195
	v_fmamk_f32 v75, v75, 0x3dd53b94, v195
	v_fmamk_f32 v76, v76, 0x3dd53b94, v195
	v_fmamk_f32 v77, v77, 0x3dd53b94, v195
	v_fmamk_f32 v78, v78, 0x3dd53b94, v195
	s_waitcnt lgkmcnt(6)
	v_mfma_f32_32x32x16_bf16 v[32:47], v[144:147], v[222:225], v[32:47]
	ds_read_b64_tr_b16 v[152:153], v183 offset:9728
	ds_read_b64_tr_b16 v[154:155], v183 offset:11776
	v_fmamk_f32 v79, v79, 0x3dd53b94, v195
	v_fmamk_f32 v80, v80, 0x3dd53b94, v195
	v_fmamk_f32 v81, v81, 0x3dd53b94, v195
	v_fmamk_f32 v82, v82, 0x3dd53b94, v195
	v_fmamk_f32 v83, v83, 0x3dd53b94, v195
	v_fmamk_f32 v84, v84, 0x3dd53b94, v195
	s_waitcnt lgkmcnt(6)
	v_mfma_f32_32x32x16_bf16 v[32:47], v[148:151], v[226:229], v[32:47]
	ds_read_b64_tr_b16 v[156:157], v183 offset:13824
	ds_read_b64_tr_b16 v[158:159], v183 offset:15872
	v_fmamk_f32 v85, v85, 0x3dd53b94, v195
	v_fmamk_f32 v86, v86, 0x3dd53b94, v195
	v_fmamk_f32 v87, v87, 0x3dd53b94, v195
	v_fmamk_f32 v88, v88, 0x3dd53b94, v195
	v_fmamk_f32 v89, v89, 0x3dd53b94, v195
	v_fmamk_f32 v90, v90, 0x3dd53b94, v195
	s_waitcnt lgkmcnt(6)
	v_mfma_f32_32x32x16_bf16 v[16:31], v[128:131], v[136:139], v[16:31]
	v_fmamk_f32 v91, v91, 0x3dd53b94, v195
	v_fmamk_f32 v92, v92, 0x3dd53b94, v195
	v_fmamk_f32 v93, v93, 0x3dd53b94, v195
	v_fmamk_f32 v94, v94, 0x3dd53b94, v195
	v_fmamk_f32 v95, v95, 0x3dd53b94, v195
	v_exp_f32_e32 v64, v64
	s_waitcnt lgkmcnt(4)
	v_mfma_f32_32x32x16_bf16 v[16:31], v[132:135], v[140:143], v[16:31]
	v_exp_f32_e32 v65, v65
	v_exp_f32_e32 v66, v66
	v_exp_f32_e32 v67, v67
	s_waitcnt lgkmcnt(2)
	v_mfma_f32_32x32x16_bf16 v[16:31], v[144:147], v[152:155], v[16:31]
	v_exp_f32_e32 v68, v68
	v_exp_f32_e32 v69, v69
	v_exp_f32_e32 v70, v70
	s_waitcnt lgkmcnt(0)
	v_mfma_f32_32x32x16_bf16 v[16:31], v[148:151], v[156:159], v[16:31]
	v_exp_f32_e32 v71, v71
	v_exp_f32_e32 v72, v72
	v_exp_f32_e32 v73, v73
	v_exp_f32_e32 v74, v74
	v_exp_f32_e32 v75, v75
	v_exp_f32_e32 v76, v76
	v_exp_f32_e32 v77, v77
	v_exp_f32_e32 v78, v78
	v_exp_f32_e32 v79, v79
	s_cmp_lg_u64 s[12:13], 0
	s_cbranch_scc0 .Lmla_nors_A
	s_and_saveexec_b64 s[20:21], s[40:41]
	ds_write_b32 v162, v193 offset:128
	s_or_b64 exec, exec, s[20:21]
	s_waitcnt lgkmcnt(0)
	v_add_u32_e32 v201, s37, v184
	ds_read_b128 v[214:217], v201 offset:128
	ds_read_b128 v[218:221], v201 offset:160
	ds_read_b128 v[222:225], v201 offset:192
	ds_read_b128 v[226:229], v201 offset:224
	s_waitcnt lgkmcnt(0)
	v_pk_mul_f32 v[0:1], v[0:1], v[214:215]
	v_pk_mul_f32 v[2:3], v[2:3], v[216:217]
	v_pk_mul_f32 v[4:5], v[4:5], v[218:219]
	v_pk_mul_f32 v[6:7], v[6:7], v[220:221]
	v_pk_mul_f32 v[8:9], v[8:9], v[222:223]
	v_pk_mul_f32 v[10:11], v[10:11], v[224:225]
	v_pk_mul_f32 v[12:13], v[12:13], v[226:227]
	v_pk_mul_f32 v[14:15], v[14:15], v[228:229]
	v_pk_mul_f32 v[48:49], v[48:49], v[214:215]
	v_pk_mul_f32 v[50:51], v[50:51], v[216:217]
	v_pk_mul_f32 v[52:53], v[52:53], v[218:219]
	v_pk_mul_f32 v[54:55], v[54:55], v[220:221]
	v_pk_mul_f32 v[56:57], v[56:57], v[222:223]
	v_pk_mul_f32 v[58:59], v[58:59], v[224:225]
	v_pk_mul_f32 v[60:61], v[60:61], v[226:227]
	v_pk_mul_f32 v[62:63], v[62:63], v[228:229]
	v_pk_mul_f32 v[32:33], v[32:33], v[214:215]
	v_pk_mul_f32 v[34:35], v[34:35], v[216:217]
	v_pk_mul_f32 v[36:37], v[36:37], v[218:219]
	v_pk_mul_f32 v[38:39], v[38:39], v[220:221]
	v_pk_mul_f32 v[40:41], v[40:41], v[222:223]
	v_pk_mul_f32 v[42:43], v[42:43], v[224:225]
	v_pk_mul_f32 v[44:45], v[44:45], v[226:227]
	v_pk_mul_f32 v[46:47], v[46:47], v[228:229]
	v_pk_mul_f32 v[16:17], v[16:17], v[214:215]
	v_pk_mul_f32 v[18:19], v[18:19], v[216:217]
	v_pk_mul_f32 v[20:21], v[20:21], v[218:219]
	v_pk_mul_f32 v[22:23], v[22:23], v[220:221]
	v_pk_mul_f32 v[24:25], v[24:25], v[222:223]
	v_pk_mul_f32 v[26:27], v[26:27], v[224:225]
	v_pk_mul_f32 v[28:29], v[28:29], v[226:227]
	v_pk_mul_f32 v[30:31], v[30:31], v[228:229]
.Lmla_nors_A:
	s_add_i32 s8, s52, 1
	s_cmp_lg_u32 s52, 2
	s_cselect_b32 s14, s8, 0
	s_add_i32 s8, s49, 1
	s_cmp_lg_u32 s49, 2
	s_cselect_b32 s15, s8, 0
	s_waitcnt vmcnt(0) lgkmcnt(0)
	s_barrier
	ds_read_b128 v[214:217], v166 offset:16384
	ds_read_b128 v[218:221], v166 offset:24576
	ds_read_b128 v[222:225], v167 offset:16384
	ds_read_b128 v[226:229], v167 offset:24576
	ds_read_b128 v[230:233], v168 offset:16384
	ds_read_b128 v[234:237], v168 offset:24576
	v_lshl_add_u32 v183, s14, 14, v161
	s_mov_b32 m0, s93
	s_lshl_b32 s8, s15, 14
	global_load_lds_dwordx4 v178, s[98:99]
	v_exp_f32_e32 v80, v80
	v_add_f32_e32 v199, v64, v65
	v_add_f32_e32 v200, v66, v67
	v_exp_f32_e32 v81, v81
	s_waitcnt lgkmcnt(4)
	v_mfma_f32_32x32x16_bf16 v[128:143], v[214:217], v[124:127], 0
	s_mov_b32 m0, s50
	s_add_i32 s12, s8, s44
	global_load_lds_dwordx4 v179, s[98:99]
	v_cvt_pk_bf16_f32 v64, v64, v65
	v_add_f32_e32 v199, v68, v199
	v_exp_f32_e32 v82, v82
	v_mfma_f32_32x32x16_bf16 v[144:159], v[218:221], v[124:127], 0
	ds_read_b128 v[214:217], v169 offset:16384
	ds_read_b128 v[218:221], v169 offset:24576
	v_cvt_pk_bf16_f32 v65, v66, v67
	v_add_f32_e32 v200, v69, v200
	v_exp_f32_e32 v83, v83
	s_waitcnt lgkmcnt(4)
	v_mfma_f32_32x32x16_bf16 v[128:143], v[222:225], v[120:123], v[128:143]
	s_mov_b32 m0, s12
	s_add_i32 s12, s8, s47
	global_load_lds_dwordx4 v180, s[98:99]
	v_add_f32_e32 v199, v70, v199
	v_cvt_pk_bf16_f32 v66, v68, v69
	v_exp_f32_e32 v84, v84
	v_mfma_f32_32x32x16_bf16 v[144:159], v[226:229], v[120:123], v[144:159]
	ds_read_b128 v[222:225], v170 offset:16384
	ds_read_b128 v[226:229], v170 offset:24576
	v_add_f32_e32 v200, v71, v200
	v_exp_f32_e32 v85, v85
	v_add_f32_e32 v199, v72, v199
	s_waitcnt lgkmcnt(4)
	v_mfma_f32_32x32x16_bf16 v[128:143], v[230:233], v[116:119], v[128:143]
	s_mov_b32 m0, s12
	s_nop 0
	global_load_lds_dwordx4 v181, s[98:99]
	v_cvt_pk_bf16_f32 v67, v70, v71
	v_exp_f32_e32 v86, v86
	v_add_f32_e32 v200, v73, v200
	v_mfma_f32_32x32x16_bf16 v[144:159], v[234:237], v[116:119], v[144:159]
	ds_read_b128 v[230:233], v171 offset:16384
	ds_read_b128 v[234:237], v171 offset:24576
	v_exp_f32_e32 v87, v87
	v_add_f32_e32 v199, v74, v199
	v_permlane32_swap_b32_e32 v64, v66
	s_waitcnt lgkmcnt(4)
	v_mfma_f32_32x32x16_bf16 v[128:143], v[214:217], v[112:115], v[128:143]
	s_mov_b32 m0, s51
	s_nop 0
	global_load_lds_dwordx4 v182, s[100:101]
	s_add_u32 s98, s98, 0x40000
	s_addc_u32 s99, s99, 0
	s_add_u32 s100, s100, 0x2000
	s_addc_u32 s101, s101, 0
	v_cvt_pk_bf16_f32 v68, v72, v73
	v_exp_f32_e32 v88, v88
	v_add_f32_e32 v200, v75, v200
	v_mfma_f32_32x32x16_bf16 v[144:159], v[218:221], v[112:115], v[144:159]
	ds_read_b128 v[214:217], v172 offset:16384
	ds_read_b128 v[218:221], v172 offset:24576
	v_exp_f32_e32 v89, v89
	v_add_f32_e32 v199, v76, v199
	v_permlane32_swap_b32_e32 v65, v67
	s_waitcnt lgkmcnt(4)
	v_mfma_f32_32x32x16_bf16 v[128:143], v[222:225], v[108:111], v[128:143]
	v_cvt_pk_bf16_f32 v69, v74, v75
	v_add_f32_e32 v200, v77, v200
	v_exp_f32_e32 v90, v90
	v_mfma_f32_32x32x16_bf16 v[144:159], v[226:229], v[108:111], v[144:159]
	ds_read_b128 v[222:225], v173 offset:16384
	ds_read_b128 v[226:229], v173 offset:24576
	v_add_f32_e32 v199, v78, v199
	v_exp_f32_e32 v91, v91
	v_cvt_pk_bf16_f32 v70, v76, v77
	s_waitcnt lgkmcnt(4)
	v_mfma_f32_32x32x16_bf16 v[128:143], v[230:233], v[104:107], v[128:143]
	v_add_f32_e32 v200, v79, v200
	v_exp_f32_e32 v92, v92
	v_add_f32_e32 v199, v80, v199
	v_mfma_f32_32x32x16_bf16 v[144:159], v[234:237], v[104:107], v[144:159]
	ds_read_b128 v[230:233], v174
	ds_read_b128 v[234:237], v174 offset:4096
	v_cvt_pk_bf16_f32 v71, v78, v79
	v_exp_f32_e32 v93, v93
	v_add_f32_e32 v200, v81, v200
	s_waitcnt lgkmcnt(4)
	v_mfma_f32_32x32x16_bf16 v[128:143], v[214:217], v[100:103], v[128:143]
	v_exp_f32_e32 v94, v94
	v_add_f32_e32 v199, v82, v199
	v_permlane32_swap_b32_e32 v68, v70
	v_mfma_f32_32x32x16_bf16 v[144:159], v[218:221], v[100:103], v[144:159]
	ds_read_b128 v[214:217], v175
	ds_read_b128 v[218:221], v175 offset:4096
	v_cvt_pk_bf16_f32 v80, v80, v81
	v_exp_f32_e32 v95, v95
	v_add_f32_e32 v200, v83, v200
	s_waitcnt lgkmcnt(4)
	v_mfma_f32_32x32x16_bf16 v[128:143], v[222:225], v[96:99], v[128:143]
	v_add_f32_e32 v199, v84, v199
	v_permlane32_swap_b32_e32 v69, v71
	v_cvt_pk_bf16_f32 v81, v82, v83
	v_add_f32_e32 v200, v85, v200
	v_mfma_f32_32x32x16_bf16 v[144:159], v[226:229], v[96:99], v[144:159]
	ds_read_b128 v[222:225], v176
	ds_read_b128 v[226:229], v176 offset:4096
	v_add_f32_e32 v199, v86, v199
	v_cvt_pk_bf16_f32 v82, v84, v85
	v_add_f32_e32 v200, v87, v200
	v_add_f32_e32 v199, v88, v199
	s_waitcnt lgkmcnt(4)
	v_mfma_f32_32x32x16_bf16 v[128:143], v[230:233], v[246:249], v[128:143]
	v_cvt_pk_bf16_f32 v83, v86, v87
	v_add_f32_e32 v200, v89, v200
	v_add_f32_e32 v199, v90, v199
	v_permlane32_swap_b32_e32 v80, v82
	v_mfma_f32_32x32x16_bf16 v[144:159], v[234:237], v[246:249], v[144:159]
	ds_read_b128 v[230:233], v177
	ds_read_b128 v[234:237], v177 offset:4096
	v_cvt_pk_bf16_f32 v84, v88, v89
	v_add_f32_e32 v200, v91, v200
	v_add_f32_e32 v199, v92, v199
	v_permlane32_swap_b32_e32 v81, v83
	s_waitcnt lgkmcnt(4)
	v_mfma_f32_32x32x16_bf16 v[128:143], v[214:217], v[250:253], v[128:143]
	v_cvt_pk_bf16_f32 v85, v90, v91
	v_add_f32_e32 v200, v93, v200
	v_add_f32_e32 v199, v94, v199
	v_cvt_pk_bf16_f32 v86, v92, v93
	v_mfma_f32_32x32x16_bf16 v[144:159], v[218:221], v[250:253], v[144:159]
	ds_read_b64_tr_b16 v[214:215], v183
	ds_read_b64_tr_b16 v[216:217], v183 offset:2048
	ds_read_b64_tr_b16 v[218:219], v183 offset:4096
	ds_read_b64_tr_b16 v[220:221], v183 offset:6144
	v_add_f32_e32 v200, v95, v200
	v_cvt_pk_bf16_f32 v87, v94, v95
	v_permlane32_swap_b32_e32 v84, v86
	v_add_f32_e32 v199, v199, v200
	s_waitcnt lgkmcnt(6)
	v_mfma_f32_32x32x16_bf16 v[128:143], v[222:225], v[186:189], v[128:143]
	v_permlane32_swap_b32_e32 v85, v87
	v_mov_b32_e32 v200, v199
	v_mfma_f32_32x32x16_bf16 v[144:159], v[226:229], v[186:189], v[144:159]
	ds_read_b64_tr_b16 v[222:223], v183 offset:8192
	ds_read_b64_tr_b16 v[224:225], v183 offset:10240
	ds_read_b64_tr_b16 v[226:227], v183 offset:12288
	ds_read_b64_tr_b16 v[228:229], v183 offset:14336
	v_permlane32_swap_b32_e32 v199, v200
	v_add_f32_e32 v199, v199, v200
	v_fma_f32 v163, v163, v193, v199
	s_waitcnt lgkmcnt(8)
	v_mfma_f32_32x32x16_bf16 v[128:143], v[230:233], v[238:241], v[128:143]
	v_mfma_f32_32x32x16_bf16 v[144:159], v[234:237], v[238:241], v[144:159]
	s_waitcnt lgkmcnt(6)
	v_mfma_f32_32x32x16_bf16 v[0:15], v[64:67], v[214:217], v[0:15]
	ds_read_b64_tr_b16 v[72:73], v183 offset:512
	ds_read_b64_tr_b16 v[74:75], v183 offset:2560
	s_waitcnt lgkmcnt(6)
	v_mfma_f32_32x32x16_bf16 v[0:15], v[68:71], v[218:221], v[0:15]
	ds_read_b64_tr_b16 v[76:77], v183 offset:4608
	ds_read_b64_tr_b16 v[78:79], v183 offset:6656
	s_waitcnt lgkmcnt(6)
	v_mfma_f32_32x32x16_bf16 v[0:15], v[80:83], v[222:225], v[0:15]
	ds_read_b64_tr_b16 v[88:89], v183 offset:8704
	ds_read_b64_tr_b16 v[90:91], v183 offset:10752
	v_max3_f32 v196, v128, v129, v130
	v_max3_f32 v197, v144, v145, v146
	v_max3_f32 v196, v196, v131, v132
	v_max3_f32 v197, v197, v147, v148
	v_max3_f32 v196, v196, v133, v134
	v_max3_f32 v197, v197, v149, v150
	s_waitcnt lgkmcnt(6)
	v_mfma_f32_32x32x16_bf16 v[0:15], v[84:87], v[226:229], v[0:15]
	ds_read_b64_tr_b16 v[92:93], v183 offset:12800
	ds_read_b64_tr_b16 v[94:95], v183 offset:14848
	v_max3_f32 v196, v196, v135, v136
	v_max3_f32 v197, v197, v151, v152
	v_max3_f32 v196, v196, v137, v138
	v_max3_f32 v197, v197, v153, v154
	v_max3_f32 v196, v196, v139, v140
	v_max3_f32 v197, v197, v155, v156
	s_waitcnt lgkmcnt(6)
	v_mfma_f32_32x32x16_bf16 v[48:63], v[64:67], v[72:75], v[48:63]
	ds_read_b64_tr_b16 v[214:215], v183 offset:1024
	ds_read_b64_tr_b16 v[216:217], v183 offset:3072
	v_max3_f32 v196, v196, v141, v142
	v_max3_f32 v197, v197, v157, v158
	v_max_f32_e32 v196, v196, v143
	v_max_f32_e32 v197, v197, v159
	v_max_f32_e32 v196, v196, v197
	v_mov_b32_e32 v197, v196
	s_waitcnt lgkmcnt(6)
	v_mfma_f32_32x32x16_bf16 v[48:63], v[68:71], v[76:79], v[48:63]
	ds_read_b64_tr_b16 v[218:219], v183 offset:5120
	ds_read_b64_tr_b16 v[220:221], v183 offset:7168
	v_permlane32_swap_b32_e32 v196, v197
	v_max_f32_e32 v196, v196, v197
	v_sub_f32_e32 v197, v196, v192
	v_cmp_ge_f32_e32 vcc, s97, v197
	s_cmp_eq_u64 vcc, exec
	s_cselect_b64 s[42:43], -1, 0
	s_waitcnt lgkmcnt(6)
	v_mfma_f32_32x32x16_bf16 v[48:63], v[80:83], v[88:91], v[48:63]
	ds_read_b64_tr_b16 v[222:223], v183 offset:9216
	ds_read_b64_tr_b16 v[224:225], v183 offset:11264
	v_max_f32_e32 v196, v192, v196
	v_sub_f32_e32 v197, v192, v196
	v_mul_f32_e32 v197, 0x3dd53b94, v197
	v_exp_f32_e32 v197, v197
	v_cndmask_b32_e64 v192, v196, v192, s[42:43]
	s_waitcnt lgkmcnt(6)
	v_mfma_f32_32x32x16_bf16 v[48:63], v[84:87], v[92:95], v[48:63]
	ds_read_b64_tr_b16 v[226:227], v183 offset:13312
	ds_read_b64_tr_b16 v[228:229], v183 offset:15360
	v_cndmask_b32_e64 v198, v197, 1.0, s[42:43]
	v_mul_f32_e32 v195, 0xbdd53b94, v192
	v_cmp_gt_f32_e64 s[12:13], 1.0, v198
	v_fmamk_f32 v128, v128, 0x3dd53b94, v195
	v_fmamk_f32 v129, v129, 0x3dd53b94, v195
	v_fmamk_f32 v130, v130, 0x3dd53b94, v195
	s_waitcnt lgkmcnt(6)
	v_mfma_f32_32x32x16_bf16 v[32:47], v[64:67], v[214:217], v[32:47]
	ds_read_b64_tr_b16 v[72:73], v183 offset:1536
	ds_read_b64_tr_b16 v[74:75], v183 offset:3584
	v_fmamk_f32 v131, v131, 0x3dd53b94, v195
	v_fmamk_f32 v132, v132, 0x3dd53b94, v195
	v_fmamk_f32 v133, v133, 0x3dd53b94, v195
	v_fmamk_f32 v134, v134, 0x3dd53b94, v195
	v_fmamk_f32 v135, v135, 0x3dd53b94, v195
	v_fmamk_f32 v136, v136, 0x3dd53b94, v195
	s_waitcnt lgkmcnt(6)
	v_mfma_f32_32x32x16_bf16 v[32:47], v[68:71], v[218:221], v[32:47]
	ds_read_b64_tr_b16 v[76:77], v183 offset:5632
	ds_read_b64_tr_b16 v[78:79], v183 offset:7680
	v_fmamk_f32 v137, v137, 0x3dd53b94, v195
	v_fmamk_f32 v138, v138, 0x3dd53b94, v195
	v_fmamk_f32 v139, v139, 0x3dd53b94, v195
	v_fmamk_f32 v140, v140, 0x3dd53b94, v195
	v_fmamk_f32 v141, v141, 0x3dd53b94, v195
	v_fmamk_f32 v142, v142, 0x3dd53b94, v195
	s_waitcnt lgkmcnt(6)
	v_mfma_f32_32x32x16_bf16 v[32:47], v[80:83], v[222:225], v[32:47]
	ds_read_b64_tr_b16 v[88:89], v183 offset:9728
	ds_read_b64_tr_b16 v[90:91], v183 offset:11776
	v_fmamk_f32 v143, v143, 0x3dd53b94, v195
	v_fmamk_f32 v144, v144, 0x3dd53b94, v195
	v_fmamk_f32 v145, v145, 0x3dd53b94, v195
	v_fmamk_f32 v146, v146, 0x3dd53b94, v195
	v_fmamk_f32 v147, v147, 0x3dd53b94, v195
	v_fmamk_f32 v148, v148, 0x3dd53b94, v195
	s_waitcnt lgkmcnt(6)
	v_mfma_f32_32x32x16_bf16 v[32:47], v[84:87], v[226:229], v[32:47]
	ds_read_b64_tr_b16 v[92:93], v183 offset:13824
	ds_read_b64_tr_b16 v[94:95], v183 offset:15872
	v_fmamk_f32 v149, v149, 0x3dd53b94, v195
	v_fmamk_f32 v150, v150, 0x3dd53b94, v195
	v_fmamk_f32 v151, v151, 0x3dd53b94, v195
	v_fmamk_f32 v152, v152, 0x3dd53b94, v195
	v_fmamk_f32 v153, v153, 0x3dd53b94, v195
	v_fmamk_f32 v154, v154, 0x3dd53b94, v195
	s_waitcnt lgkmcnt(6)
	v_mfma_f32_32x32x16_bf16 v[16:31], v[64:67], v[72:75], v[16:31]
	v_fmamk_f32 v155, v155, 0x3dd53b94, v195
	v_fmamk_f32 v156, v156, 0x3dd53b94, v195
	v_fmamk_f32 v157, v157, 0x3dd53b94, v195
	v_fmamk_f32 v158, v158, 0x3dd53b94, v195
	v_fmamk_f32 v159, v159, 0x3dd53b94, v195
	v_exp_f32_e32 v128, v128
	s_waitcnt lgkmcnt(4)
	v_mfma_f32_32x32x16_bf16 v[16:31], v[68:71], v[76:79], v[16:31]
	v_exp_f32_e32 v129, v129
	v_exp_f32_e32 v130, v130
	v_exp_f32_e32 v131, v131
	s_waitcnt lgkmcnt(2)
	v_mfma_f32_32x32x16_bf16 v[16:31], v[80:83], v[88:91], v[16:31]
	v_exp_f32_e32 v132, v132
	v_exp_f32_e32 v133, v133
	v_exp_f32_e32 v134, v134
	s_waitcnt lgkmcnt(0)
	v_mfma_f32_32x32x16_bf16 v[16:31], v[84:87], v[92:95], v[16:31]
	v_exp_f32_e32 v135, v135
	v_exp_f32_e32 v136, v136
	v_exp_f32_e32 v137, v137
	v_exp_f32_e32 v138, v138
	v_exp_f32_e32 v139, v139
	v_exp_f32_e32 v140, v140
	v_exp_f32_e32 v141, v141
	v_exp_f32_e32 v142, v142
	v_exp_f32_e32 v143, v143
	s_cmp_lg_u64 s[12:13], 0
	s_cbranch_scc0 .Lmla_nors_B
	s_and_saveexec_b64 s[20:21], s[40:41]
	ds_write_b32 v162, v198 offset:128
	s_or_b64 exec, exec, s[20:21]
	s_waitcnt lgkmcnt(0)
	v_add_u32_e32 v201, s37, v184
	ds_read_b128 v[214:217], v201 offset:128
	ds_read_b128 v[218:221], v201 offset:160
	ds_read_b128 v[222:225], v201 offset:192
	ds_read_b128 v[226:229], v201 offset:224
	s_waitcnt lgkmcnt(0)
	v_pk_mul_f32 v[0:1], v[0:1], v[214:215]
	v_pk_mul_f32 v[2:3], v[2:3], v[216:217]
	v_pk_mul_f32 v[4:5], v[4:5], v[218:219]
	v_pk_mul_f32 v[6:7], v[6:7], v[220:221]
	v_pk_mul_f32 v[8:9], v[8:9], v[222:223]
	v_pk_mul_f32 v[10:11], v[10:11], v[224:225]
	v_pk_mul_f32 v[12:13], v[12:13], v[226:227]
	v_pk_mul_f32 v[14:15], v[14:15], v[228:229]
	v_pk_mul_f32 v[48:49], v[48:49], v[214:215]
	v_pk_mul_f32 v[50:51], v[50:51], v[216:217]
	v_pk_mul_f32 v[52:53], v[52:53], v[218:219]
	v_pk_mul_f32 v[54:55], v[54:55], v[220:221]
	v_pk_mul_f32 v[56:57], v[56:57], v[222:223]
	v_pk_mul_f32 v[58:59], v[58:59], v[224:225]
	v_pk_mul_f32 v[60:61], v[60:61], v[226:227]
	v_pk_mul_f32 v[62:63], v[62:63], v[228:229]
	v_pk_mul_f32 v[32:33], v[32:33], v[214:215]
	v_pk_mul_f32 v[34:35], v[34:35], v[216:217]
	v_pk_mul_f32 v[36:37], v[36:37], v[218:219]
	v_pk_mul_f32 v[38:39], v[38:39], v[220:221]
	v_pk_mul_f32 v[40:41], v[40:41], v[222:223]
	v_pk_mul_f32 v[42:43], v[42:43], v[224:225]
	v_pk_mul_f32 v[44:45], v[44:45], v[226:227]
	v_pk_mul_f32 v[46:47], v[46:47], v[228:229]
	v_pk_mul_f32 v[16:17], v[16:17], v[214:215]
	v_pk_mul_f32 v[18:19], v[18:19], v[216:217]
	v_pk_mul_f32 v[20:21], v[20:21], v[218:219]
	v_pk_mul_f32 v[22:23], v[22:23], v[220:221]
	v_pk_mul_f32 v[24:25], v[24:25], v[222:223]
	v_pk_mul_f32 v[26:27], v[26:27], v[224:225]
	v_pk_mul_f32 v[28:29], v[28:29], v[226:227]
	v_pk_mul_f32 v[30:31], v[30:31], v[228:229]
.Lmla_nors_B:
	s_add_i32 s8, s14, 1
	s_cmp_lg_u32 s14, 2
	s_cselect_b32 s52, s8, 0
	s_add_i32 s8, s15, 1
	s_cmp_lg_u32 s15, 2
	s_cselect_b32 s49, s8, 0
	s_waitcnt vmcnt(0) lgkmcnt(0)
	s_barrier
	s_add_i32 s48, s48, 2
	s_cmp_lt_u32 s48, 61
	s_cbranch_scc1 .Lmla_loop
	v_mov_b32_e32 v236, v128
	v_mov_b32_e32 v238, v129
	v_mov_b32_e32 v234, v130
	v_mov_b32_e32 v237, v131
	v_mov_b32_e32 v233, v132
	v_mov_b32_e32 v235, v133
	v_mov_b32_e32 v231, v134
	v_mov_b32_e32 v232, v135
	v_mov_b32_e32 v228, v136
	v_mov_b32_e32 v230, v137
	v_mov_b32_e32 v227, v138
	v_mov_b32_e32 v229, v139
	v_mov_b32_e32 v224, v140
	v_mov_b32_e32 v226, v141
	v_mov_b32_e32 v223, v142
	v_mov_b32_e32 v225, v143
	v_mov_b32_e32 v134, v152
	v_mov_b32_e32 v135, v153
	v_mov_b32_e32 v132, v154
	v_mov_b32_e32 v133, v155
	v_mov_b32_e32 v130, v156
	v_mov_b32_e32 v131, v157
	v_mov_b32_e32 v128, v158
	v_mov_b32_e32 v129, v159
	v_mov_b32_e32 v158, v144
	v_mov_b32_e32 v159, v145
	v_mov_b32_e32 v156, v146
	v_mov_b32_e32 v157, v147
	v_mov_b32_e32 v154, v148
	v_mov_b32_e32 v155, v149
	v_mov_b32_e32 v152, v150
	v_mov_b32_e32 v153, v151
	v_mov_b32_e32 v222, v192
	v_mov_b32_e32 v144, v198
	v_add_u32_e32 v199, 0x8000, v166
	v_add_u32_e32 v200, 0x8000, v167
	v_add_u32_e32 v201, 0x8000, v168
	v_add_u32_e32 v202, 0x8000, v169
	v_add_u32_e32 v214, 0x8000, v170
	v_add_u32_e32 v215, 0x8000, v171
	v_add_u32_e32 v216, 0x8000, v172
	v_add_u32_e32 v217, 0x8000, v173
	v_add_u32_e32 v219, 0x2000, v174
	v_add_u32_e32 v218, 0x2000, v175
	v_add_u32_e32 v220, 0x2000, v176
	v_add_u32_e32 v221, 0x2000, v177

	.amdhsa_kernel _Z14fwd_megakernel6Params
		.amdhsa_group_segment_fixed_size 0
		.amdhsa_private_segment_fixed_size 0
		.amdhsa_kernarg_size 528
		.amdhsa_user_sgpr_count 2
		.amdhsa_user_sgpr_dispatch_ptr 0
		.amdhsa_user_sgpr_queue_ptr 0
		.amdhsa_user_sgpr_kernarg_segment_ptr 1
		.amdhsa_user_sgpr_dispatch_id 0
		.amdhsa_user_sgpr_kernarg_preload_length 0
		.amdhsa_user_sgpr_kernarg_preload_offset 0
		.amdhsa_user_sgpr_private_segment_size 0
		.amdhsa_uses_dynamic_stack 0
		.amdhsa_enable_private_segment 0
		.amdhsa_system_sgpr_workgroup_id_x 1
		.amdhsa_system_sgpr_workgroup_id_y 0
		.amdhsa_system_sgpr_workgroup_id_z 0
		.amdhsa_system_sgpr_workgroup_info 0
		.amdhsa_system_vgpr_workitem_id 2
		.amdhsa_next_free_vgpr 256
		.amdhsa_next_free_sgpr 102
		.amdhsa_accum_offset 256
		.amdhsa_reserve_vcc 1
		.amdhsa_float_round_mode_32 0
		.amdhsa_float_round_mode_16_64 0
		.amdhsa_float_denorm_mode_32 3
		.amdhsa_float_denorm_mode_16_64 3
		.amdhsa_dx10_clamp 1
		.amdhsa_ieee_mode 1
		.amdhsa_fp16_overflow 0
		.amdhsa_tg_split 0
		.amdhsa_exception_fp_ieee_invalid_op 0
		.amdhsa_exception_fp_denorm_src 0
		.amdhsa_exception_fp_ieee_div_zero 0
		.amdhsa_exception_fp_ieee_overflow 0
		.amdhsa_exception_fp_ieee_underflow 0
		.amdhsa_exception_fp_ieee_inexact 0
		.amdhsa_exception_int_div_zero 0
	.end_amdhsa_kernel

amdhsa.kernels:
  - .agpr_count:     0
    .args:
      - .offset:         0
        .size:           272
        .value_kind:     by_value
      - .offset:         272
        .size:           4
        .value_kind:     hidden_block_count_x
      - .offset:         276
        .size:           4
        .value_kind:     hidden_block_count_y
      - .offset:         280
        .size:           4
        .value_kind:     hidden_block_count_z
      - .offset:         284
        .size:           2
        .value_kind:     hidden_group_size_x
      - .offset:         286
        .size:           2
        .value_kind:     hidden_group_size_y
      - .offset:         288
        .size:           2
        .value_kind:     hidden_group_size_z
      - .offset:         290
        .size:           2
        .value_kind:     hidden_remainder_x
      - .offset:         292
        .size:           2
        .value_kind:     hidden_remainder_y
      - .offset:         294
        .size:           2
        .value_kind:     hidden_remainder_z
      - .offset:         312
        .size:           8
        .value_kind:     hidden_global_offset_x
      - .offset:         320
        .size:           8
        .value_kind:     hidden_global_offset_y
      - .offset:         328
        .size:           8
        .value_kind:     hidden_global_offset_z
      - .offset:         336
        .size:           2
        .value_kind:     hidden_grid_dims
      - .offset:         360
        .size:           8
        .value_kind:     hidden_multigrid_sync_arg
      - .offset:         392
        .size:           4
        .value_kind:     hidden_dynamic_lds_size
    .group_segment_fixed_size: 0
    .kernarg_segment_align: 8
    .kernarg_segment_size: 528
    .language:       OpenCL C
    .language_version:
      - 2
      - 0
    .max_flat_workgroup_size: 512
    .name:           _Z14fwd_megakernel6Params
    .private_segment_fixed_size: 0
    .sgpr_count:     108
    .sgpr_spill_count: 121
    .symbol:         _Z14fwd_megakernel6Params.kd
    .uniform_work_group_size: 1
    .uses_dynamic_stack: false
    .vgpr_count:     256
    .vgpr_spill_count: 0
    .wavefront_size: 64
